# s21 + cross_plain: cross-attention outputs stored write-back (same-XCD consumer in P3, no write-back at barrier 2 when placement verified)
# speedup vs baseline: 1.0104x; 1.0001x over previous
.LBB0_346:
	v_or_b32_e32 v134, s14, v40
	v_mov_b64_e32 v[0:1], s[60:61]
	v_or_b32_e32 v3, s15, v41
	v_mad_u64_u32 v[0:1], s[14:15], v134, s23, v[0:1]
	v_mov_b32_e32 v2, v1
	v_mad_u64_u32 v[2:3], s[14:15], v3, s23, v[2:3]
	v_mov_b32_e32 v1, v2
	v_lshl_add_u64 v[0:1], v[0:1], 0, s[8:9]
	v_lshl_add_u64 v[62:63], v[18:19], 1, v[0:1]
	v_lshl_add_u64 v[58:59], v[62:63], 0, s[10:11]
	global_load_dwordx4 v[0:3], v[38:39], off offset:400
	global_load_dwordx4 v[4:7], v[36:37], off offset:400
	global_load_dwordx4 v[8:11], v[36:37], off offset:384
	global_load_dwordx4 v[12:15], v[38:39], off offset:384
	global_load_dwordx4 v[42:45], v[36:37], off offset:272
	global_load_dwordx4 v[46:49], v[38:39], off offset:272
	global_load_dwordx4 v[50:53], v[58:59], off offset:192
	global_load_dwordx4 v[54:57], v[58:59], off offset:128
	s_nop 0
	global_load_dwordx4 v[58:61], v[58:59], off offset:64
	v_add_co_u32_e32 v62, vcc, s24, v62
	s_waitcnt vmcnt(7)
	v_pk_mul_f32 v[142:143], v[4:5], v[0:1]
	v_addc_co_u32_e32 v63, vcc, 0, v63, vcc
	global_load_dwordx4 v[62:65], v[62:63], off
	s_nop 0
	global_load_dwordx4 v[66:69], v[36:37], off offset:256
	global_load_dwordx4 v[70:73], v[38:39], off offset:256
	global_load_dwordx4 v[74:77], v[36:37], off offset:144
	global_load_dwordx4 v[78:81], v[36:37], off offset:128
	global_load_dwordx4 v[82:85], v[38:39], off offset:144
	global_load_dwordx4 v[86:89], v[38:39], off offset:128
	global_load_dwordx4 v[90:93], v[36:37], off offset:16
	global_load_dwordx4 v[94:97], v[36:37], off
	global_load_dwordx4 v[98:101], v[38:39], off offset:16
	global_load_dwordx4 v[136:139], v[38:39], off
	v_pk_mul_f32 v[140:141], v[6:7], v[2:3]
	s_waitcnt vmcnt(16)
	v_pk_mul_f32 v[12:13], v[8:9], v[12:13]
	s_waitcnt vmcnt(14)
	v_pk_mul_f32 v[8:9], v[44:45], v[48:49]
	s_waitcnt vmcnt(13)
	v_lshlrev_b32_e32 v144, 16, v53
	v_and_b32_e32 v145, 0xffff0000, v53
	v_lshlrev_b32_e32 v146, 16, v52
	v_and_b32_e32 v147, 0xffff0000, v52
	v_lshlrev_b32_e32 v52, 16, v51
	v_and_b32_e32 v53, 0xffff0000, v51
	v_lshlrev_b32_e32 v148, 16, v50
	v_and_b32_e32 v149, 0xffff0000, v50
	s_waitcnt vmcnt(12)
	v_lshlrev_b32_e32 v48, 16, v55
	v_and_b32_e32 v49, 0xffff0000, v55
	v_lshlrev_b32_e32 v50, 16, v54
	v_and_b32_e32 v51, 0xffff0000, v54
	s_waitcnt vmcnt(11)
	v_lshlrev_b32_e32 v54, 16, v61
	v_and_b32_e32 v55, 0xffff0000, v61
	v_lshlrev_b32_e32 v6, 16, v60
	v_and_b32_e32 v7, 0xffff0000, v60
	v_pk_mul_f32 v[14:15], v[10:11], v[14:15]
	v_lshlrev_b32_e32 v44, 16, v57
	v_and_b32_e32 v45, 0xffff0000, v57
	v_lshlrev_b32_e32 v10, 16, v56
	v_and_b32_e32 v11, 0xffff0000, v56
	v_lshlrev_b32_e32 v56, 16, v59
	v_and_b32_e32 v57, 0xffff0000, v59
	v_lshlrev_b32_e32 v4, 16, v58
	v_and_b32_e32 v5, 0xffff0000, v58
	v_pk_mul_f32 v[168:169], v[4:5], v[4:5]
	v_pk_mul_f32 v[166:167], v[56:57], v[56:57]
	v_pk_mul_f32 v[164:165], v[6:7], v[6:7]
	v_pk_mul_f32 v[162:163], v[54:55], v[54:55]
	v_pk_mul_f32 v[160:161], v[50:51], v[50:51]
	v_pk_mul_f32 v[158:159], v[48:49], v[48:49]
	v_pk_mul_f32 v[156:157], v[10:11], v[10:11]
	v_pk_mul_f32 v[154:155], v[44:45], v[44:45]
	v_pk_mul_f32 v[152:153], v[148:149], v[148:149]
	v_pk_mul_f32 v[150:151], v[52:53], v[52:53]
	v_pk_mul_f32 v[42:43], v[42:43], v[46:47]
	s_waitcnt vmcnt(10)
	v_lshlrev_b32_e32 v0, 16, v62
	v_and_b32_e32 v1, 0xffff0000, v62
	v_lshlrev_b32_e32 v60, 16, v63
	v_and_b32_e32 v61, 0xffff0000, v63
	v_pk_mul_f32 v[176:177], v[0:1], v[0:1]
	v_pk_mul_f32 v[174:175], v[60:61], v[60:61]
	v_add_f32_e32 v135, v177, v176
	v_lshlrev_b32_e32 v2, 16, v64
	v_and_b32_e32 v3, 0xffff0000, v64
	v_add_f32_e32 v135, v135, v174
	v_pk_mul_f32 v[172:173], v[2:3], v[2:3]
	v_add_f32_e32 v135, v175, v135
	v_lshlrev_b32_e32 v58, 16, v65
	v_and_b32_e32 v59, 0xffff0000, v65
	v_add_f32_e32 v135, v172, v135
	v_pk_mul_f32 v[170:171], v[58:59], v[58:59]
	v_add_f32_e32 v135, v173, v135
	v_add_f32_e32 v135, v170, v135
	v_add_f32_e32 v135, v171, v135
	v_add_f32_e32 v135, v135, v168
	v_add_f32_e32 v135, v169, v135
	v_add_f32_e32 v135, v135, v166
	v_add_f32_e32 v135, v167, v135
	v_add_f32_e32 v135, v164, v135
	v_add_f32_e32 v135, v165, v135
	v_add_f32_e32 v135, v162, v135
	v_add_f32_e32 v135, v163, v135
	v_add_f32_e32 v135, v135, v160
	v_add_f32_e32 v135, v161, v135
	v_add_f32_e32 v135, v135, v158
	v_add_f32_e32 v135, v159, v135
	v_add_f32_e32 v135, v156, v135
	v_add_f32_e32 v135, v157, v135
	v_add_f32_e32 v135, v154, v135
	v_add_f32_e32 v135, v155, v135
	v_add_f32_e32 v135, v135, v152
	v_add_f32_e32 v135, v153, v135
	v_add_f32_e32 v135, v135, v150
	v_pk_mul_f32 v[64:65], v[146:147], v[146:147]
	v_add_f32_e32 v135, v151, v135
	v_add_f32_e32 v64, v64, v135
	v_pk_mul_f32 v[62:63], v[144:145], v[144:145]
	v_add_f32_e32 v64, v65, v64
	v_add_f32_e32 v62, v62, v64
	v_add_f32_e32 v135, v63, v62
	ds_bpermute_b32 v150, v109, v135
	s_waitcnt vmcnt(5)
	v_pk_mul_f32 v[64:65], v[76:77], v[84:85]
	v_pk_mul_f32 v[62:63], v[66:67], v[70:71]
	v_pk_mul_f32 v[66:67], v[74:75], v[82:83]
	v_pk_mul_f32 v[46:47], v[68:69], v[72:73]
	s_waitcnt lgkmcnt(0)
	v_add_f32_e32 v76, v135, v150
	ds_bpermute_b32 v77, v110, v76
	s_waitcnt vmcnt(4)
	v_pk_mul_f32 v[68:69], v[80:81], v[88:89]
	v_pk_mul_f32 v[70:71], v[78:79], v[86:87]
	s_waitcnt vmcnt(1)
	v_pk_mul_f32 v[72:73], v[92:93], v[100:101]
	s_waitcnt vmcnt(0)
	v_pk_mul_f32 v[78:79], v[94:95], v[136:137]
	s_waitcnt lgkmcnt(0)
	v_add_f32_e32 v74, v76, v77
	v_fmamk_f32 v74, v74, 0x3c000000, v132
	v_mul_f32_e32 v75, 0x4b800000, v74
	v_cmp_gt_f32_e32 vcc, s22, v74
	v_pk_mul_f32 v[76:77], v[96:97], v[138:139]
	s_nop 0
	v_cndmask_b32_e32 v74, v74, v75, vcc
	v_rsq_f32_e32 v80, v74
	v_pk_mul_f32 v[74:75], v[90:91], v[98:99]
	v_mul_f32_e32 v81, 0x45800000, v80
	v_cndmask_b32_e32 v80, v80, v81, vcc
	v_mul_f32_e32 v80, 0x3db504f3, v80
	v_pk_mul_f32 v[78:79], v[80:81], v[78:79] op_sel_hi:[0,1]
	v_pk_mul_f32 v[76:77], v[80:81], v[76:77] op_sel_hi:[0,1]
	v_pk_mul_f32 v[74:75], v[80:81], v[74:75] op_sel_hi:[0,1]
	v_pk_mul_f32 v[72:73], v[80:81], v[72:73] op_sel_hi:[0,1]
	v_pk_mul_f32 v[0:1], v[78:79], v[0:1]
	v_pk_mul_f32 v[60:61], v[76:77], v[60:61]
	v_pk_mul_f32 v[2:3], v[74:75], v[2:3]
	v_pk_mul_f32 v[58:59], v[72:73], v[58:59]
	v_cvt_pk_bf16_f32 v0, v0, v1
	v_cvt_pk_bf16_f32 v1, v60, v61
	v_cvt_pk_bf16_f32 v2, v2, v3
	v_cvt_pk_bf16_f32 v3, v58, v59
	v_pk_mul_f32 v[58:59], v[80:81], v[70:71] op_sel_hi:[0,1]
	v_pk_mul_f32 v[60:61], v[80:81], v[68:69] op_sel_hi:[0,1]
	v_pk_mul_f32 v[4:5], v[58:59], v[4:5]
	v_pk_mul_f32 v[56:57], v[60:61], v[56:57]
	v_cvt_pk_bf16_f32 v4, v4, v5
	v_cvt_pk_bf16_f32 v5, v56, v57
	v_pk_mul_f32 v[42:43], v[80:81], v[42:43] op_sel_hi:[0,1]
	v_pk_mul_f32 v[56:57], v[80:81], v[8:9] op_sel_hi:[0,1]
	v_pk_mul_f32 v[10:11], v[42:43], v[10:11]
	v_pk_mul_f32 v[42:43], v[56:57], v[44:45]
	v_pk_mul_f32 v[66:67], v[80:81], v[66:67] op_sel_hi:[0,1]
	v_pk_mul_f32 v[64:65], v[80:81], v[64:65] op_sel_hi:[0,1]
	v_cvt_pk_bf16_f32 v10, v10, v11
	v_cvt_pk_bf16_f32 v11, v42, v43
	ds_read_b128 v[42:45], v129
	v_pk_mul_f32 v[6:7], v[66:67], v[6:7]
	v_pk_mul_f32 v[54:55], v[64:65], v[54:55]
	v_cvt_pk_bf16_f32 v6, v6, v7
	v_cvt_pk_bf16_f32 v7, v54, v55
	v_pk_mul_f32 v[54:55], v[80:81], v[62:63] op_sel_hi:[0,1]
	v_pk_mul_f32 v[46:47], v[80:81], v[46:47] op_sel_hi:[0,1]
	v_pk_mul_f32 v[8:9], v[54:55], v[50:51]
	v_pk_mul_f32 v[46:47], v[46:47], v[48:49]
	v_cvt_pk_bf16_f32 v8, v8, v9
	v_cvt_pk_bf16_f32 v9, v46, v47
	ds_read_b128 v[46:49], v129 offset:64
	v_pk_mul_f32 v[14:15], v[80:81], v[14:15] op_sel_hi:[0,1]
	v_pk_mul_f32 v[14:15], v[14:15], v[52:53]
	ds_read_b128 v[50:53], v129 offset:128
	s_waitcnt lgkmcnt(2)
	v_mfma_f32_16x16x32_bf16 v[42:45], v[42:45], v[0:3], 0
	v_mul_f32_e64 v12, v80, v12
	v_mul_f32_e64 v13, v80, v13
	v_pk_mul_f32 v[54:55], v[80:81], v[142:143] op_sel_hi:[0,1]
	v_pk_mul_f32 v[12:13], v[12:13], v[148:149]
	s_waitcnt lgkmcnt(1)
	v_mfma_f32_16x16x32_bf16 v[42:45], v[46:49], v[4:7], v[42:45]
	v_cvt_pk_bf16_f32 v12, v12, v13
	v_cvt_pk_bf16_f32 v13, v14, v15
	v_pk_mul_f32 v[14:15], v[54:55], v[146:147]
	ds_read_b128 v[54:57], v129 offset:192
	v_pk_mul_f32 v[58:59], v[80:81], v[140:141] op_sel_hi:[0,1]
	v_pk_mul_f32 v[46:47], v[58:59], v[144:145]
	s_waitcnt lgkmcnt(1)
	v_mfma_f32_16x16x32_bf16 v[42:45], v[50:53], v[8:11], v[42:45]
	v_cvt_pk_bf16_f32 v14, v14, v15
	v_cvt_pk_bf16_f32 v15, v46, v47
	v_add_u32_e32 v46, 0, v111
	v_add_u32_e32 v135, 0x22000, v46
	ds_read_b128 v[46:49], v135
	s_waitcnt lgkmcnt(1)
	v_mfma_f32_16x16x32_bf16 v[50:53], v[54:57], v[12:15], v[42:45]
	s_waitcnt lgkmcnt(0)
	s_nop 6
	v_pk_mul_f32 v[42:43], v[48:49], v[52:53]
	v_pk_mul_f32 v[60:61], v[46:47], v[50:51]
	ds_read_b128 v[44:47], v129 offset:4352
	ds_read_b128 v[48:51], v129 offset:4416
	ds_read_b128 v[52:55], v129 offset:4480
	s_waitcnt lgkmcnt(2)
	v_mfma_f32_16x16x32_bf16 v[44:47], v[44:47], v[0:3], 0
	s_waitcnt lgkmcnt(1)
	v_mfma_f32_16x16x32_bf16 v[44:47], v[48:51], v[4:7], v[44:47]
	ds_read_b128 v[48:51], v129 offset:4544
	s_waitcnt lgkmcnt(1)
	v_mfma_f32_16x16x32_bf16 v[44:47], v[52:55], v[8:11], v[44:47]
	ds_read_b128 v[52:55], v135 offset:64
	s_waitcnt lgkmcnt(1)
	v_mfma_f32_16x16x32_bf16 v[46:49], v[48:51], v[12:15], v[44:47]
	s_waitcnt lgkmcnt(0)
	s_nop 6
	v_pk_mul_f32 v[44:45], v[54:55], v[48:49]
	v_pk_mul_f32 v[64:65], v[52:53], v[46:47]
	ds_read_b128 v[46:49], v129 offset:8704
	ds_read_b128 v[50:53], v129 offset:8768
	ds_read_b128 v[54:57], v129 offset:8832
	s_waitcnt lgkmcnt(2)
	v_mfma_f32_16x16x32_bf16 v[46:49], v[46:49], v[0:3], 0
	s_waitcnt lgkmcnt(1)
	v_mfma_f32_16x16x32_bf16 v[46:49], v[50:53], v[4:7], v[46:49]
	ds_read_b128 v[50:53], v129 offset:8896
	s_waitcnt lgkmcnt(1)
	v_mfma_f32_16x16x32_bf16 v[46:49], v[54:57], v[8:11], v[46:49]
	ds_read_b128 v[54:57], v135 offset:128
	s_waitcnt lgkmcnt(1)
	v_mfma_f32_16x16x32_bf16 v[48:51], v[50:53], v[12:15], v[46:49]
	s_waitcnt lgkmcnt(0)
	s_nop 6
	v_pk_mul_f32 v[46:47], v[56:57], v[50:51]
	v_pk_mul_f32 v[68:69], v[54:55], v[48:49]
	ds_read_b128 v[48:51], v129 offset:13056
	ds_read_b128 v[52:55], v129 offset:13120
	ds_read_b128 v[56:59], v129 offset:13184
	s_waitcnt lgkmcnt(2)
	v_mfma_f32_16x16x32_bf16 v[48:51], v[48:51], v[0:3], 0
	s_waitcnt lgkmcnt(1)
	v_mfma_f32_16x16x32_bf16 v[48:51], v[52:55], v[4:7], v[48:51]
	ds_read_b128 v[52:55], v129 offset:13248
	s_waitcnt lgkmcnt(1)
	v_mfma_f32_16x16x32_bf16 v[48:51], v[56:59], v[8:11], v[48:51]
	ds_read_b128 v[56:59], v135 offset:192
	s_waitcnt lgkmcnt(1)
	v_mfma_f32_16x16x32_bf16 v[50:53], v[52:55], v[12:15], v[48:51]
	s_waitcnt lgkmcnt(0)
	s_nop 6
	v_pk_mul_f32 v[48:49], v[58:59], v[52:53]
	v_pk_mul_f32 v[72:73], v[56:57], v[50:51]
	ds_read_b128 v[50:53], v129 offset:17408
	ds_read_b128 v[54:57], v129 offset:17472
	ds_read_b128 v[74:77], v129 offset:17536
	s_waitcnt lgkmcnt(2)
	v_mfma_f32_16x16x32_bf16 v[50:53], v[50:53], v[0:3], 0
	s_waitcnt lgkmcnt(1)
	v_mfma_f32_16x16x32_bf16 v[50:53], v[54:57], v[4:7], v[50:53]
	ds_read_b128 v[54:57], v129 offset:17600
	s_waitcnt lgkmcnt(1)
	v_mfma_f32_16x16x32_bf16 v[50:53], v[74:77], v[8:11], v[50:53]
	ds_read_b128 v[74:77], v135 offset:256
	s_waitcnt lgkmcnt(1)
	v_mfma_f32_16x16x32_bf16 v[52:55], v[54:57], v[12:15], v[50:53]
	s_waitcnt lgkmcnt(0)
	s_nop 6
	v_pk_mul_f32 v[50:51], v[76:77], v[54:55]
	v_pk_mul_f32 v[76:77], v[74:75], v[52:53]
	ds_read_b128 v[52:55], v129 offset:21760
	ds_read_b128 v[56:59], v129 offset:21824
	ds_read_b128 v[78:81], v129 offset:21888
	s_waitcnt lgkmcnt(2)
	v_mfma_f32_16x16x32_bf16 v[52:55], v[52:55], v[0:3], 0
	s_waitcnt lgkmcnt(1)
	v_mfma_f32_16x16x32_bf16 v[52:55], v[56:59], v[4:7], v[52:55]
	ds_read_b128 v[56:59], v129 offset:21952
	s_waitcnt lgkmcnt(1)
	v_mfma_f32_16x16x32_bf16 v[52:55], v[78:81], v[8:11], v[52:55]
	ds_read_b128 v[78:81], v135 offset:320
	s_waitcnt lgkmcnt(1)
	v_mfma_f32_16x16x32_bf16 v[54:57], v[56:59], v[12:15], v[52:55]
	s_waitcnt lgkmcnt(0)
	s_nop 6
	v_pk_mul_f32 v[52:53], v[80:81], v[56:57]
	v_pk_mul_f32 v[80:81], v[78:79], v[54:55]
	ds_read_b128 v[54:57], v129 offset:26112
	ds_read_b128 v[82:85], v129 offset:26176
	ds_read_b128 v[86:89], v129 offset:26240
	s_waitcnt lgkmcnt(2)
	v_mfma_f32_16x16x32_bf16 v[54:57], v[54:57], v[0:3], 0
	s_waitcnt lgkmcnt(1)
	v_mfma_f32_16x16x32_bf16 v[54:57], v[82:85], v[4:7], v[54:57]
	ds_read_b128 v[82:85], v129 offset:26304
	s_waitcnt lgkmcnt(1)
	v_mfma_f32_16x16x32_bf16 v[54:57], v[86:89], v[8:11], v[54:57]
	ds_read_b128 v[86:89], v135 offset:384
	s_waitcnt lgkmcnt(1)
	v_mfma_f32_16x16x32_bf16 v[56:59], v[82:85], v[12:15], v[54:57]
	s_waitcnt lgkmcnt(0)
	s_nop 6
	v_pk_mul_f32 v[54:55], v[88:89], v[58:59]
	v_pk_mul_f32 v[84:85], v[86:87], v[56:57]
	ds_read_b128 v[56:59], v129 offset:30464
	ds_read_b128 v[86:89], v129 offset:30528
	ds_read_b128 v[90:93], v129 offset:30592
	s_waitcnt lgkmcnt(2)
	v_mfma_f32_16x16x32_bf16 v[56:59], v[56:59], v[0:3], 0
	s_waitcnt lgkmcnt(1)
	v_mfma_f32_16x16x32_bf16 v[56:59], v[86:89], v[4:7], v[56:59]
	ds_read_b128 v[86:89], v129 offset:30656
	s_waitcnt lgkmcnt(1)
	v_mfma_f32_16x16x32_bf16 v[56:59], v[90:93], v[8:11], v[56:59]
	ds_read_b128 v[90:93], v135 offset:448
	s_waitcnt lgkmcnt(1)
	v_mfma_f32_16x16x32_bf16 v[86:89], v[86:89], v[12:15], v[56:59]
	s_waitcnt lgkmcnt(0)
	s_nop 6
	v_pk_mul_f32 v[56:57], v[92:93], v[88:89]
	v_pk_mul_f32 v[86:87], v[90:91], v[86:87]
	ds_read_b128 v[88:91], v129 offset:34816
	ds_read_b128 v[92:95], v129 offset:34880
	ds_read_b128 v[96:99], v129 offset:34944
	s_waitcnt lgkmcnt(2)
	v_mfma_f32_16x16x32_bf16 v[88:91], v[88:91], v[0:3], 0
	s_waitcnt lgkmcnt(1)
	v_mfma_f32_16x16x32_bf16 v[88:91], v[92:95], v[4:7], v[88:91]
	ds_read_b128 v[92:95], v129 offset:35008
	s_waitcnt lgkmcnt(1)
	v_mfma_f32_16x16x32_bf16 v[88:91], v[96:99], v[8:11], v[88:91]
	ds_read_b128 v[96:99], v135 offset:512
	s_waitcnt lgkmcnt(1)
	v_mfma_f32_16x16x32_bf16 v[88:91], v[92:95], v[12:15], v[88:91]
	s_waitcnt lgkmcnt(0)
	s_nop 6
	v_pk_mul_f32 v[58:59], v[98:99], v[90:91]
	v_pk_mul_f32 v[88:89], v[96:97], v[88:89]
	ds_read_b128 v[90:93], v129 offset:39168
	ds_read_b128 v[94:97], v129 offset:39232
	ds_read_b128 v[98:101], v129 offset:39296
	s_waitcnt lgkmcnt(2)
	v_mfma_f32_16x16x32_bf16 v[90:93], v[90:93], v[0:3], 0
	s_waitcnt lgkmcnt(1)
	v_mfma_f32_16x16x32_bf16 v[90:93], v[94:97], v[4:7], v[90:93]
	ds_read_b128 v[94:97], v129 offset:39360
	s_waitcnt lgkmcnt(1)
	v_mfma_f32_16x16x32_bf16 v[90:93], v[98:101], v[8:11], v[90:93]
	ds_read_b128 v[98:101], v135 offset:576
	s_waitcnt lgkmcnt(1)
	v_mfma_f32_16x16x32_bf16 v[90:93], v[94:97], v[12:15], v[90:93]
	s_waitcnt lgkmcnt(0)
	s_nop 6
	v_pk_mul_f32 v[62:63], v[100:101], v[92:93]
	v_pk_mul_f32 v[90:91], v[98:99], v[90:91]
	ds_read_b128 v[92:95], v129 offset:43520
	ds_read_b128 v[96:99], v129 offset:43584
	ds_read_b128 v[136:139], v129 offset:43648
	s_waitcnt lgkmcnt(2)
	v_mfma_f32_16x16x32_bf16 v[92:95], v[92:95], v[0:3], 0
	s_waitcnt lgkmcnt(1)
	v_mfma_f32_16x16x32_bf16 v[92:95], v[96:99], v[4:7], v[92:95]
	ds_read_b128 v[96:99], v129 offset:43712
	s_waitcnt lgkmcnt(1)
	v_mfma_f32_16x16x32_bf16 v[92:95], v[136:139], v[8:11], v[92:95]
	ds_read_b128 v[136:139], v135 offset:640
	s_waitcnt lgkmcnt(1)
	v_mfma_f32_16x16x32_bf16 v[92:95], v[96:99], v[12:15], v[92:95]
	s_waitcnt lgkmcnt(0)
	s_nop 6
	v_pk_mul_f32 v[66:67], v[138:139], v[94:95]
	v_pk_mul_f32 v[92:93], v[136:137], v[92:93]
	ds_read_b128 v[94:97], v129 offset:47872
	ds_read_b128 v[98:101], v129 offset:47936
	ds_read_b128 v[136:139], v129 offset:48000
	s_waitcnt lgkmcnt(2)
	v_mfma_f32_16x16x32_bf16 v[94:97], v[94:97], v[0:3], 0
	s_waitcnt lgkmcnt(1)
	v_mfma_f32_16x16x32_bf16 v[94:97], v[98:101], v[4:7], v[94:97]
	ds_read_b128 v[98:101], v129 offset:48064
	s_waitcnt lgkmcnt(1)
	v_mfma_f32_16x16x32_bf16 v[94:97], v[136:139], v[8:11], v[94:97]
	ds_read_b128 v[136:139], v135 offset:704
	s_waitcnt lgkmcnt(1)
	v_mfma_f32_16x16x32_bf16 v[94:97], v[98:101], v[12:15], v[94:97]
	s_waitcnt lgkmcnt(0)
	s_nop 6
	v_pk_mul_f32 v[70:71], v[138:139], v[96:97]
	v_pk_mul_f32 v[94:95], v[136:137], v[94:95]
	ds_read_b128 v[96:99], v129 offset:52224
	ds_read_b128 v[136:139], v129 offset:52288
	ds_read_b128 v[140:143], v129 offset:52352
	s_waitcnt lgkmcnt(2)
	v_mfma_f32_16x16x32_bf16 v[96:99], v[96:99], v[0:3], 0
	s_waitcnt lgkmcnt(1)
	v_mfma_f32_16x16x32_bf16 v[96:99], v[136:139], v[4:7], v[96:99]
	ds_read_b128 v[136:139], v129 offset:52416
	s_waitcnt lgkmcnt(1)
	v_mfma_f32_16x16x32_bf16 v[96:99], v[140:143], v[8:11], v[96:99]
	ds_read_b128 v[140:143], v135 offset:768
	s_waitcnt lgkmcnt(1)
	v_mfma_f32_16x16x32_bf16 v[96:99], v[136:139], v[12:15], v[96:99]
	s_waitcnt lgkmcnt(0)
	s_nop 6
	v_pk_mul_f32 v[74:75], v[142:143], v[98:99]
	v_pk_mul_f32 v[96:97], v[140:141], v[96:97]
	ds_read_b128 v[98:101], v129 offset:56576
	ds_read_b128 v[136:139], v129 offset:56640
	ds_read_b128 v[140:143], v129 offset:56704
	s_waitcnt lgkmcnt(2)
	v_mfma_f32_16x16x32_bf16 v[98:101], v[98:101], v[0:3], 0
	s_waitcnt lgkmcnt(1)
	v_mfma_f32_16x16x32_bf16 v[98:101], v[136:139], v[4:7], v[98:101]
	ds_read_b128 v[136:139], v129 offset:56768
	s_waitcnt lgkmcnt(1)
	v_mfma_f32_16x16x32_bf16 v[98:101], v[140:143], v[8:11], v[98:101]
	ds_read_b128 v[140:143], v135 offset:832
	s_waitcnt lgkmcnt(1)
	v_mfma_f32_16x16x32_bf16 v[98:101], v[136:139], v[12:15], v[98:101]
	s_waitcnt lgkmcnt(0)
	s_nop 6
	v_pk_mul_f32 v[78:79], v[142:143], v[100:101]
	v_pk_mul_f32 v[98:99], v[140:141], v[98:99]
	ds_read_b128 v[136:139], v129 offset:60928
	ds_read_b128 v[140:143], v129 offset:60992
	ds_read_b128 v[144:147], v129 offset:61056
	s_waitcnt lgkmcnt(2)
	v_mfma_f32_16x16x32_bf16 v[136:139], v[136:139], v[0:3], 0
	s_waitcnt lgkmcnt(1)
	v_mfma_f32_16x16x32_bf16 v[136:139], v[140:143], v[4:7], v[136:139]
	ds_read_b128 v[140:143], v129 offset:61120
	s_waitcnt lgkmcnt(1)
	v_mfma_f32_16x16x32_bf16 v[136:139], v[144:147], v[8:11], v[136:139]
	ds_read_b128 v[144:147], v135 offset:896
	s_waitcnt lgkmcnt(1)
	v_mfma_f32_16x16x32_bf16 v[136:139], v[140:143], v[12:15], v[136:139]
	s_waitcnt lgkmcnt(0)
	s_nop 6
	v_pk_mul_f32 v[82:83], v[146:147], v[138:139]
	v_pk_mul_f32 v[100:101], v[144:145], v[136:137]
	ds_read_b128 v[136:139], v129 offset:65280
	ds_read_b128 v[140:143], v129 offset:65344
	s_waitcnt lgkmcnt(1)
	v_mfma_f32_16x16x32_bf16 v[0:3], v[136:139], v[0:3], 0
	ds_read_b128 v[136:139], v129 offset:65408
	s_waitcnt lgkmcnt(1)
	v_mfma_f32_16x16x32_bf16 v[0:3], v[140:143], v[4:7], v[0:3]
	ds_read_b128 v[4:7], v129 offset:65472
	s_waitcnt lgkmcnt(1)
	v_mfma_f32_16x16x32_bf16 v[0:3], v[136:139], v[8:11], v[0:3]
	ds_read_b128 v[8:11], v135 offset:960
	s_waitcnt lgkmcnt(1)
	v_mfma_f32_16x16x32_bf16 v[2:5], v[4:7], v[12:15], v[0:3]
	s_waitcnt lgkmcnt(0)
	s_nop 6
	v_pk_mul_f32 v[0:1], v[10:11], v[4:5]
	v_pk_mul_f32 v[2:3], v[8:9], v[2:3]
	v_max_f32_e32 v4, v42, v43
	v_max_f32_e32 v5, v44, v45
	v_max3_f32 v4, v60, v61, v4
	v_max3_f32 v5, v64, v65, v5
	v_max3_f32 v4, v4, s25, v5
	v_max_f32_e32 v5, v46, v47
	v_max_f32_e32 v6, v48, v49
	v_max3_f32 v5, v68, v69, v5
	v_max3_f32 v6, v72, v73, v6
	v_max3_f32 v4, v4, v5, v6
	v_max_f32_e32 v5, v50, v51
	v_max_f32_e32 v6, v52, v53
	v_max3_f32 v5, v76, v77, v5
	v_max3_f32 v6, v80, v81, v6
	v_max3_f32 v4, v4, v5, v6
	v_max_f32_e32 v5, v54, v55
	v_max_f32_e32 v6, v56, v57
	v_max3_f32 v5, v84, v85, v5
	v_max3_f32 v6, v86, v87, v6
	v_max3_f32 v4, v4, v5, v6
	v_max_f32_e32 v5, v58, v59
	v_max_f32_e32 v6, v62, v63
	v_max3_f32 v5, v88, v89, v5
	v_max3_f32 v6, v90, v91, v6
	v_max3_f32 v4, v4, v5, v6
	v_max_f32_e32 v5, v66, v67
	v_max_f32_e32 v6, v70, v71
	v_max3_f32 v5, v92, v93, v5
	v_max3_f32 v6, v94, v95, v6
	v_max3_f32 v4, v4, v5, v6
	v_max_f32_e32 v5, v74, v75
	v_max_f32_e32 v6, v78, v79
	v_max3_f32 v5, v96, v97, v5
	v_max3_f32 v6, v98, v99, v6
	v_max3_f32 v4, v4, v5, v6
	v_max_f32_e32 v5, v82, v83
	v_max_f32_e32 v6, v0, v1
	v_max3_f32 v5, v100, v101, v5
	v_max3_f32 v6, v2, v3, v6
	v_max3_f32 v4, v4, v5, v6
	ds_bpermute_b32 v5, v109, v4
	s_waitcnt lgkmcnt(0)
	v_max_f32_e32 v5, v5, v5
	v_max_f32_e32 v4, v4, v5
	ds_bpermute_b32 v5, v110, v4
	s_waitcnt lgkmcnt(0)
	v_max_f32_e32 v5, v5, v5
	v_max_f32_e32 v135, v4, v5
	v_sub_f32_e32 v5, v61, v135
	v_mul_f32_e32 v5, 0x3fb8aa3b, v5
	v_exp_f32_e32 v61, v5
	v_sub_f32_e32 v5, v42, v135
	v_mul_f32_e32 v5, 0x3fb8aa3b, v5
	v_exp_f32_e32 v42, v5
	v_sub_f32_e32 v5, v43, v135
	v_mul_f32_e32 v5, 0x3fb8aa3b, v5
	v_exp_f32_e32 v136, v5
	v_sub_f32_e32 v5, v64, v135
	v_mul_f32_e32 v5, 0x3fb8aa3b, v5
	v_exp_f32_e32 v64, v5
	v_sub_f32_e32 v5, v65, v135
	v_mul_f32_e32 v5, 0x3fb8aa3b, v5
	v_exp_f32_e32 v65, v5
	v_sub_f32_e32 v5, v44, v135
	v_mul_f32_e32 v5, 0x3fb8aa3b, v5
	v_exp_f32_e32 v137, v5
	v_sub_f32_e32 v5, v45, v135
	v_mul_f32_e32 v5, 0x3fb8aa3b, v5
	v_exp_f32_e32 v138, v5
	v_sub_f32_e32 v5, v68, v135
	v_mul_f32_e32 v5, 0x3fb8aa3b, v5
	v_exp_f32_e32 v139, v5
	v_sub_f32_e32 v5, v69, v135
	v_mul_f32_e32 v5, 0x3fb8aa3b, v5
	v_exp_f32_e32 v140, v5
	v_sub_f32_e32 v5, v46, v135
	v_mul_f32_e32 v5, 0x3fb8aa3b, v5
	v_exp_f32_e32 v141, v5
	v_sub_f32_e32 v5, v47, v135
	v_mul_f32_e32 v5, 0x3fb8aa3b, v5
	v_exp_f32_e32 v142, v5
	v_sub_f32_e32 v5, v72, v135
	v_mul_f32_e32 v5, 0x3fb8aa3b, v5
	v_exp_f32_e32 v143, v5
	v_sub_f32_e32 v5, v73, v135
	v_mul_f32_e32 v5, 0x3fb8aa3b, v5
	v_exp_f32_e32 v144, v5
	v_sub_f32_e32 v5, v48, v135
	v_mul_f32_e32 v5, 0x3fb8aa3b, v5
	v_exp_f32_e32 v145, v5
	v_sub_f32_e32 v5, v49, v135
	v_mul_f32_e32 v5, 0x3fb8aa3b, v5
	v_exp_f32_e32 v146, v5
	v_sub_f32_e32 v5, v76, v135
	v_mul_f32_e32 v5, 0x3fb8aa3b, v5
	v_exp_f32_e32 v147, v5
	v_sub_f32_e32 v5, v77, v135
	v_mul_f32_e32 v5, 0x3fb8aa3b, v5
	v_exp_f32_e32 v148, v5
	v_sub_f32_e32 v5, v50, v135
	v_mul_f32_e32 v5, 0x3fb8aa3b, v5
	v_exp_f32_e32 v149, v5
	v_sub_f32_e32 v5, v51, v135
	v_mul_f32_e32 v5, 0x3fb8aa3b, v5
	v_exp_f32_e32 v150, v5
	v_sub_f32_e32 v5, v80, v135
	v_mul_f32_e32 v5, 0x3fb8aa3b, v5
	v_exp_f32_e32 v151, v5
	v_sub_f32_e32 v5, v81, v135
	v_mul_f32_e32 v5, 0x3fb8aa3b, v5
	v_exp_f32_e32 v152, v5
	v_sub_f32_e32 v5, v52, v135
	v_mul_f32_e32 v5, 0x3fb8aa3b, v5
	v_exp_f32_e32 v153, v5
	v_sub_f32_e32 v5, v53, v135
	v_mul_f32_e32 v5, 0x3fb8aa3b, v5
	v_exp_f32_e32 v154, v5
	v_sub_f32_e32 v5, v84, v135
	v_mul_f32_e32 v5, 0x3fb8aa3b, v5
	v_exp_f32_e32 v155, v5
	v_sub_f32_e32 v5, v85, v135
	v_mul_f32_e32 v5, 0x3fb8aa3b, v5
	v_sub_f32_e32 v4, v60, v135
	v_exp_f32_e32 v156, v5
	v_sub_f32_e32 v5, v54, v135
	v_mul_f32_e32 v4, 0x3fb8aa3b, v4
	v_mul_f32_e32 v5, 0x3fb8aa3b, v5
	v_exp_f32_e32 v60, v4
	v_exp_f32_e32 v157, v5
	v_sub_f32_e32 v5, v55, v135
	v_mul_f32_e32 v5, 0x3fb8aa3b, v5
	v_exp_f32_e32 v158, v5
	v_sub_f32_e32 v5, v86, v135
	v_mul_f32_e32 v5, 0x3fb8aa3b, v5
	v_add_f32_e32 v4, 0, v60
	v_exp_f32_e32 v159, v5
	v_sub_f32_e32 v5, v87, v135
	v_add_f32_e32 v4, v4, v61
	v_mul_f32_e32 v5, 0x3fb8aa3b, v5
	v_add_f32_e32 v4, v4, v42
	v_exp_f32_e32 v160, v5
	v_sub_f32_e32 v5, v56, v135
	v_add_f32_e32 v4, v4, v136
	v_mul_f32_e32 v5, 0x3fb8aa3b, v5
	v_add_f32_e32 v4, v4, v64
	v_exp_f32_e32 v161, v5
	v_sub_f32_e32 v5, v57, v135
	v_add_f32_e32 v4, v4, v65
	v_mul_f32_e32 v5, 0x3fb8aa3b, v5
	v_add_f32_e32 v4, v4, v137
	v_exp_f32_e32 v162, v5
	v_sub_f32_e32 v5, v88, v135
	v_add_f32_e32 v4, v4, v138
	v_mul_f32_e32 v5, 0x3fb8aa3b, v5
	v_add_f32_e32 v4, v4, v139
	v_exp_f32_e32 v163, v5
	v_sub_f32_e32 v5, v89, v135
	v_add_f32_e32 v4, v4, v140
	v_mul_f32_e32 v5, 0x3fb8aa3b, v5
	v_add_f32_e32 v4, v4, v141
	v_exp_f32_e32 v164, v5
	v_sub_f32_e32 v5, v58, v135
	v_add_f32_e32 v4, v4, v142
	v_mul_f32_e32 v5, 0x3fb8aa3b, v5
	v_add_f32_e32 v4, v4, v143
	v_exp_f32_e32 v165, v5
	v_sub_f32_e32 v5, v59, v135
	v_add_f32_e32 v4, v4, v144
	v_mul_f32_e32 v5, 0x3fb8aa3b, v5
	v_add_f32_e32 v4, v4, v145
	v_exp_f32_e32 v166, v5
	v_sub_f32_e32 v5, v90, v135
	v_add_f32_e32 v4, v4, v146
	v_mul_f32_e32 v5, 0x3fb8aa3b, v5
	v_add_f32_e32 v4, v4, v147
	v_exp_f32_e32 v167, v5
	v_sub_f32_e32 v5, v91, v135
	v_add_f32_e32 v4, v4, v148
	v_mul_f32_e32 v5, 0x3fb8aa3b, v5
	v_add_f32_e32 v4, v4, v149
	v_exp_f32_e32 v168, v5
	v_sub_f32_e32 v5, v62, v135
	v_add_f32_e32 v4, v4, v150
	v_mul_f32_e32 v5, 0x3fb8aa3b, v5
	v_add_f32_e32 v4, v4, v151
	v_exp_f32_e32 v169, v5
	v_sub_f32_e32 v5, v63, v135
	v_add_f32_e32 v4, v4, v152
	v_mul_f32_e32 v5, 0x3fb8aa3b, v5
	v_add_f32_e32 v4, v4, v153
	v_exp_f32_e32 v170, v5
	v_sub_f32_e32 v5, v92, v135
	v_add_f32_e32 v4, v4, v154
	v_mul_f32_e32 v5, 0x3fb8aa3b, v5
	v_add_f32_e32 v4, v4, v155
	v_exp_f32_e32 v43, v5
	v_sub_f32_e32 v5, v93, v135
	v_add_f32_e32 v4, v4, v156
	v_mul_f32_e32 v5, 0x3fb8aa3b, v5
	v_add_f32_e32 v4, v4, v157
	v_exp_f32_e32 v44, v5
	v_sub_f32_e32 v5, v66, v135
	v_add_f32_e32 v4, v4, v158
	v_mul_f32_e32 v5, 0x3fb8aa3b, v5
	v_add_f32_e32 v4, v4, v159
	v_exp_f32_e32 v171, v5
	v_sub_f32_e32 v5, v67, v135
	v_add_f32_e32 v4, v4, v160
	v_mul_f32_e32 v5, 0x3fb8aa3b, v5
	v_add_f32_e32 v4, v4, v161
	v_exp_f32_e32 v172, v5
	v_sub_f32_e32 v5, v94, v135
	v_add_f32_e32 v4, v4, v162
	v_mul_f32_e32 v5, 0x3fb8aa3b, v5
	v_add_f32_e32 v4, v4, v163
	v_exp_f32_e32 v45, v5
	v_sub_f32_e32 v5, v95, v135
	v_add_f32_e32 v4, v4, v164
	v_mul_f32_e32 v5, 0x3fb8aa3b, v5
	v_add_f32_e32 v4, v4, v165
	v_exp_f32_e32 v173, v5
	v_sub_f32_e32 v5, v70, v135
	v_add_f32_e32 v4, v4, v166
	v_mul_f32_e32 v5, 0x3fb8aa3b, v5
	v_add_f32_e32 v4, v4, v167
	v_exp_f32_e32 v174, v5
	v_sub_f32_e32 v5, v71, v135
	v_add_f32_e32 v4, v4, v168
	v_mul_f32_e32 v5, 0x3fb8aa3b, v5
	v_add_f32_e32 v4, v4, v169
	v_exp_f32_e32 v175, v5
	v_sub_f32_e32 v5, v96, v135
	v_add_f32_e32 v4, v4, v170
	v_mul_f32_e32 v5, 0x3fb8aa3b, v5
	v_add_f32_e32 v4, v4, v43
	v_exp_f32_e32 v8, v5
	v_sub_f32_e32 v5, v97, v135
	v_add_f32_e32 v4, v4, v44
	v_mul_f32_e32 v5, 0x3fb8aa3b, v5
	v_add_f32_e32 v4, v4, v171
	v_exp_f32_e32 v9, v5
	v_sub_f32_e32 v5, v74, v135
	v_add_f32_e32 v4, v4, v172
	v_mul_f32_e32 v5, 0x3fb8aa3b, v5
	v_add_f32_e32 v4, v4, v45
	v_exp_f32_e32 v11, v5
	v_sub_f32_e32 v5, v75, v135
	v_add_f32_e32 v4, v4, v173
	v_mul_f32_e32 v5, 0x3fb8aa3b, v5
	v_add_f32_e32 v4, v4, v174
	v_exp_f32_e32 v12, v5
	v_sub_f32_e32 v5, v98, v135
	v_add_f32_e32 v4, v4, v175
	v_mul_f32_e32 v5, 0x3fb8aa3b, v5
	v_add_f32_e32 v4, v4, v8
	v_exp_f32_e32 v10, v5
	v_add_f32_e32 v4, v4, v9
	v_add_f32_e32 v4, v4, v11
	v_add_f32_e32 v4, v4, v12
	v_add_f32_e32 v5, v4, v10
	v_sub_f32_e32 v4, v99, v135
	v_mul_f32_e32 v4, 0x3fb8aa3b, v4
	v_exp_f32_e32 v13, v4
	v_sub_f32_e32 v4, v78, v135
	v_mul_f32_e32 v4, 0x3fb8aa3b, v4
	v_exp_f32_e32 v14, v4
	v_sub_f32_e32 v4, v79, v135
	v_mul_f32_e32 v4, 0x3fb8aa3b, v4
	v_exp_f32_e32 v15, v4
	v_sub_f32_e32 v4, v100, v135
	v_mul_f32_e32 v4, 0x3fb8aa3b, v4
	v_exp_f32_e32 v4, v4
	v_add_f32_e32 v5, v5, v13
	v_add_f32_e32 v5, v5, v14
	v_add_f32_e32 v5, v5, v15
	v_add_f32_e32 v46, v5, v4
	v_sub_f32_e32 v5, v101, v135
	v_mul_f32_e32 v5, 0x3fb8aa3b, v5
	v_sub_f32_e32 v6, v82, v135
	v_exp_f32_e32 v5, v5
	v_mul_f32_e32 v6, 0x3fb8aa3b, v6
	v_sub_f32_e32 v7, v83, v135
	v_exp_f32_e32 v6, v6
	v_mul_f32_e32 v7, 0x3fb8aa3b, v7
	v_sub_f32_e32 v2, v2, v135
	v_exp_f32_e32 v7, v7
	v_mul_f32_e32 v2, 0x3fb8aa3b, v2
	v_sub_f32_e32 v3, v3, v135
	v_sub_f32_e32 v0, v0, v135
	v_exp_f32_e32 v2, v2
	v_mul_f32_e32 v3, 0x3fb8aa3b, v3
	v_mul_f32_e32 v0, 0x3fb8aa3b, v0
	v_add_f32_e32 v46, v46, v5
	v_cvt_pk_bf16_f32 v47, v42, v136
	v_exp_f32_e32 v3, v3
	v_exp_f32_e32 v42, v0
	v_sub_f32_e32 v0, v1, v135
	v_add_f32_e32 v46, v46, v6
	v_mul_f32_e32 v0, 0x3fb8aa3b, v0
	v_add_f32_e32 v46, v46, v7
	v_exp_f32_e32 v1, v0
	v_add_f32_e32 v82, v46, v2
	v_add_f32_e32 v0, v82, v3
	v_add_f32_e32 v0, v0, v42
	v_add_f32_e32 v0, v0, v1
	ds_bpermute_b32 v82, v109, v0
	v_cvt_pk_bf16_f32 v46, v60, v61
	ds_read_b64_tr_b16 v[52:53], v131
	ds_read_b64_tr_b16 v[50:51], v130
	v_cvt_pk_bf16_f32 v48, v64, v65
	ds_read_b64_tr_b16 v[56:57], v131 offset:32
	ds_read_b64_tr_b16 v[54:55], v130 offset:32
	ds_read_b64_tr_b16 v[58:59], v130 offset:64
	ds_read_b64_tr_b16 v[62:63], v130 offset:96
	ds_read_b64_tr_b16 v[60:61], v131 offset:64
	ds_read_b64_tr_b16 v[64:65], v131 offset:96
	s_waitcnt lgkmcnt(8)
	v_add_f32_e32 v0, v0, v82
	ds_read_b64_tr_b16 v[66:67], v130 offset:128
	ds_read_b64_tr_b16 v[68:69], v131 offset:128
	ds_read_b64_tr_b16 v[72:73], v131 offset:160
	ds_read_b64_tr_b16 v[70:71], v130 offset:160
	ds_read_b64_tr_b16 v[74:75], v130 offset:192
	ds_read_b64_tr_b16 v[78:79], v130 offset:224
	ds_read_b64_tr_b16 v[76:77], v131 offset:192
	ds_read_b64_tr_b16 v[80:81], v131 offset:224
	ds_bpermute_b32 v82, v110, v0
	v_cvt_pk_bf16_f32 v49, v137, v138
	s_waitcnt lgkmcnt(0)
	v_add_f32_e32 v0, v0, v82
	v_mfma_f32_16x16x32_bf16 v[50:53], v[50:53], v[46:49], 0
	v_mfma_f32_16x16x32_bf16 v[54:57], v[54:57], v[46:49], 0
	v_mfma_f32_16x16x32_bf16 v[58:61], v[58:61], v[46:49], 0
	v_mfma_f32_16x16x32_bf16 v[62:65], v[62:65], v[46:49], 0
	v_mfma_f32_16x16x32_bf16 v[66:69], v[66:69], v[46:49], 0
	v_mfma_f32_16x16x32_bf16 v[70:73], v[70:73], v[46:49], 0
	v_mfma_f32_16x16x32_bf16 v[74:77], v[74:77], v[46:49], 0
	v_mfma_f32_16x16x32_bf16 v[46:49], v[78:81], v[46:49], 0
	ds_read_b64_tr_b16 v[84:85], v131 offset:8704
	ds_read_b64_tr_b16 v[82:83], v130 offset:8704
	ds_read_b64_tr_b16 v[88:89], v131 offset:8736
	ds_read_b64_tr_b16 v[86:87], v130 offset:8736
	ds_read_b64_tr_b16 v[90:91], v130 offset:8768
	ds_read_b64_tr_b16 v[94:95], v130 offset:8800
	ds_read_b64_tr_b16 v[92:93], v131 offset:8768
	ds_read_b64_tr_b16 v[96:97], v131 offset:8800
	v_cvt_pk_bf16_f32 v78, v139, v140
	v_cvt_pk_bf16_f32 v79, v141, v142
	v_cvt_pk_bf16_f32 v80, v143, v144
	v_cvt_pk_bf16_f32 v81, v145, v146
	s_waitcnt lgkmcnt(6)
	s_nop 0
	v_mfma_f32_16x16x32_bf16 v[50:53], v[82:85], v[78:81], v[50:53]
	ds_read_b64_tr_b16 v[82:83], v130 offset:8832
	ds_read_b64_tr_b16 v[84:85], v131 offset:8832
	s_waitcnt lgkmcnt(6)
	v_mfma_f32_16x16x32_bf16 v[54:57], v[86:89], v[78:81], v[54:57]
	s_waitcnt lgkmcnt(3)
	v_mfma_f32_16x16x32_bf16 v[58:61], v[90:93], v[78:81], v[58:61]
	s_waitcnt lgkmcnt(2)
	v_mfma_f32_16x16x32_bf16 v[62:65], v[94:97], v[78:81], v[62:65]
	ds_read_b64_tr_b16 v[88:89], v131 offset:8864
	ds_read_b64_tr_b16 v[86:87], v130 offset:8864
	ds_read_b64_tr_b16 v[90:91], v130 offset:8896
	ds_read_b64_tr_b16 v[94:95], v130 offset:8928
	ds_read_b64_tr_b16 v[92:93], v131 offset:8896
	ds_read_b64_tr_b16 v[96:97], v131 offset:8928
	s_waitcnt lgkmcnt(6)
	v_mfma_f32_16x16x32_bf16 v[66:69], v[82:85], v[78:81], v[66:69]
	s_waitcnt lgkmcnt(4)
	v_mfma_f32_16x16x32_bf16 v[70:73], v[86:89], v[78:81], v[70:73]
	s_waitcnt lgkmcnt(1)
	v_mfma_f32_16x16x32_bf16 v[74:77], v[90:93], v[78:81], v[74:77]
	s_waitcnt lgkmcnt(0)
	v_mfma_f32_16x16x32_bf16 v[46:49], v[94:97], v[78:81], v[46:49]
	ds_read_b64_tr_b16 v[84:85], v131 offset:17408
	ds_read_b64_tr_b16 v[82:83], v130 offset:17408
	ds_read_b64_tr_b16 v[88:89], v131 offset:17440
	ds_read_b64_tr_b16 v[86:87], v130 offset:17440
	ds_read_b64_tr_b16 v[90:91], v130 offset:17472
	ds_read_b64_tr_b16 v[94:95], v130 offset:17504
	ds_read_b64_tr_b16 v[92:93], v131 offset:17472
	ds_read_b64_tr_b16 v[96:97], v131 offset:17504
	v_cvt_pk_bf16_f32 v78, v147, v148
	v_cvt_pk_bf16_f32 v79, v149, v150
	v_cvt_pk_bf16_f32 v80, v151, v152
	v_cvt_pk_bf16_f32 v81, v153, v154
	s_waitcnt lgkmcnt(6)
	s_nop 0
	v_mfma_f32_16x16x32_bf16 v[50:53], v[82:85], v[78:81], v[50:53]
	ds_read_b64_tr_b16 v[82:83], v130 offset:17536
	ds_read_b64_tr_b16 v[84:85], v131 offset:17536
	s_waitcnt lgkmcnt(6)
	v_mfma_f32_16x16x32_bf16 v[54:57], v[86:89], v[78:81], v[54:57]
	s_waitcnt lgkmcnt(3)
	v_mfma_f32_16x16x32_bf16 v[58:61], v[90:93], v[78:81], v[58:61]
	s_waitcnt lgkmcnt(2)
	v_mfma_f32_16x16x32_bf16 v[62:65], v[94:97], v[78:81], v[62:65]
	ds_read_b64_tr_b16 v[88:89], v131 offset:17568
	ds_read_b64_tr_b16 v[86:87], v130 offset:17568
	ds_read_b64_tr_b16 v[90:91], v130 offset:17600
	ds_read_b64_tr_b16 v[94:95], v130 offset:17632
	ds_read_b64_tr_b16 v[92:93], v131 offset:17600
	ds_read_b64_tr_b16 v[96:97], v131 offset:17632
	s_waitcnt lgkmcnt(6)
	v_mfma_f32_16x16x32_bf16 v[66:69], v[82:85], v[78:81], v[66:69]
	s_waitcnt lgkmcnt(4)
	v_mfma_f32_16x16x32_bf16 v[70:73], v[86:89], v[78:81], v[70:73]
	s_waitcnt lgkmcnt(1)
	v_mfma_f32_16x16x32_bf16 v[74:77], v[90:93], v[78:81], v[74:77]
	s_waitcnt lgkmcnt(0)
	v_mfma_f32_16x16x32_bf16 v[46:49], v[94:97], v[78:81], v[46:49]
	ds_read_b64_tr_b16 v[84:85], v131 offset:26112
	ds_read_b64_tr_b16 v[82:83], v130 offset:26112
	ds_read_b64_tr_b16 v[88:89], v131 offset:26144
	ds_read_b64_tr_b16 v[86:87], v130 offset:26144
	ds_read_b64_tr_b16 v[90:91], v130 offset:26176
	ds_read_b64_tr_b16 v[94:95], v130 offset:26208
	ds_read_b64_tr_b16 v[92:93], v131 offset:26176
	ds_read_b64_tr_b16 v[96:97], v131 offset:26208
	v_cvt_pk_bf16_f32 v78, v155, v156
	v_cvt_pk_bf16_f32 v79, v157, v158
	v_cvt_pk_bf16_f32 v80, v159, v160
	v_cvt_pk_bf16_f32 v81, v161, v162
	s_waitcnt lgkmcnt(6)
	s_nop 0
	v_mfma_f32_16x16x32_bf16 v[50:53], v[82:85], v[78:81], v[50:53]
	ds_read_b64_tr_b16 v[82:83], v130 offset:26240
	ds_read_b64_tr_b16 v[84:85], v131 offset:26240
	s_waitcnt lgkmcnt(6)
	v_mfma_f32_16x16x32_bf16 v[54:57], v[86:89], v[78:81], v[54:57]
	s_waitcnt lgkmcnt(3)
	v_mfma_f32_16x16x32_bf16 v[58:61], v[90:93], v[78:81], v[58:61]
	s_waitcnt lgkmcnt(2)
	v_mfma_f32_16x16x32_bf16 v[62:65], v[94:97], v[78:81], v[62:65]
	ds_read_b64_tr_b16 v[88:89], v131 offset:26272
	ds_read_b64_tr_b16 v[86:87], v130 offset:26272
	ds_read_b64_tr_b16 v[90:91], v130 offset:26304
	ds_read_b64_tr_b16 v[94:95], v130 offset:26336
	ds_read_b64_tr_b16 v[92:93], v131 offset:26304
	ds_read_b64_tr_b16 v[96:97], v131 offset:26336
	s_waitcnt lgkmcnt(6)
	v_mfma_f32_16x16x32_bf16 v[66:69], v[82:85], v[78:81], v[66:69]
	s_waitcnt lgkmcnt(4)
	v_mfma_f32_16x16x32_bf16 v[70:73], v[86:89], v[78:81], v[70:73]
	s_waitcnt lgkmcnt(1)
	v_mfma_f32_16x16x32_bf16 v[74:77], v[90:93], v[78:81], v[74:77]
	s_waitcnt lgkmcnt(0)
	v_mfma_f32_16x16x32_bf16 v[46:49], v[94:97], v[78:81], v[46:49]
	ds_read_b64_tr_b16 v[84:85], v131 offset:34816
	ds_read_b64_tr_b16 v[82:83], v130 offset:34816
	ds_read_b64_tr_b16 v[88:89], v131 offset:34848
	ds_read_b64_tr_b16 v[86:87], v130 offset:34848
	ds_read_b64_tr_b16 v[90:91], v130 offset:34880
	ds_read_b64_tr_b16 v[94:95], v130 offset:34912
	ds_read_b64_tr_b16 v[92:93], v131 offset:34880
	ds_read_b64_tr_b16 v[96:97], v131 offset:34912
	v_cvt_pk_bf16_f32 v78, v163, v164
	v_cvt_pk_bf16_f32 v79, v165, v166
	v_cvt_pk_bf16_f32 v80, v167, v168
	v_cvt_pk_bf16_f32 v81, v169, v170
	s_waitcnt lgkmcnt(6)
	s_nop 0
	v_mfma_f32_16x16x32_bf16 v[50:53], v[82:85], v[78:81], v[50:53]
	ds_read_b64_tr_b16 v[82:83], v130 offset:34944
	ds_read_b64_tr_b16 v[84:85], v131 offset:34944
	s_waitcnt lgkmcnt(6)
	v_mfma_f32_16x16x32_bf16 v[54:57], v[86:89], v[78:81], v[54:57]
	s_waitcnt lgkmcnt(3)
	v_mfma_f32_16x16x32_bf16 v[58:61], v[90:93], v[78:81], v[58:61]
	s_waitcnt lgkmcnt(2)
	v_mfma_f32_16x16x32_bf16 v[62:65], v[94:97], v[78:81], v[62:65]
	ds_read_b64_tr_b16 v[88:89], v131 offset:34976
	ds_read_b64_tr_b16 v[86:87], v130 offset:34976
	ds_read_b64_tr_b16 v[90:91], v130 offset:35008
	ds_read_b64_tr_b16 v[94:95], v130 offset:35040
	ds_read_b64_tr_b16 v[92:93], v131 offset:35008
	ds_read_b64_tr_b16 v[96:97], v131 offset:35040
	s_waitcnt lgkmcnt(6)
	v_mfma_f32_16x16x32_bf16 v[66:69], v[82:85], v[78:81], v[66:69]
	s_waitcnt lgkmcnt(4)
	v_mfma_f32_16x16x32_bf16 v[70:73], v[86:89], v[78:81], v[70:73]
	s_waitcnt lgkmcnt(1)
	v_mfma_f32_16x16x32_bf16 v[74:77], v[90:93], v[78:81], v[74:77]
	s_waitcnt lgkmcnt(0)
	v_mfma_f32_16x16x32_bf16 v[46:49], v[94:97], v[78:81], v[46:49]
	ds_read_b64_tr_b16 v[84:85], v131 offset:43520
	ds_read_b64_tr_b16 v[82:83], v130 offset:43520
	ds_read_b64_tr_b16 v[88:89], v131 offset:43552
	ds_read_b64_tr_b16 v[86:87], v130 offset:43552
	ds_read_b64_tr_b16 v[90:91], v130 offset:43584
	ds_read_b64_tr_b16 v[94:95], v130 offset:43616
	ds_read_b64_tr_b16 v[92:93], v131 offset:43584
	ds_read_b64_tr_b16 v[96:97], v131 offset:43616
	v_cvt_pk_bf16_f32 v78, v43, v44
	v_cvt_pk_bf16_f32 v79, v171, v172
	v_cvt_pk_bf16_f32 v80, v45, v173
	v_cvt_pk_bf16_f32 v81, v174, v175
	s_waitcnt lgkmcnt(6)
	s_nop 0
	v_mfma_f32_16x16x32_bf16 v[50:53], v[82:85], v[78:81], v[50:53]
	ds_read_b64_tr_b16 v[82:83], v130 offset:43648
	ds_read_b64_tr_b16 v[84:85], v131 offset:43648
	s_waitcnt lgkmcnt(6)
	v_mfma_f32_16x16x32_bf16 v[54:57], v[86:89], v[78:81], v[54:57]
	s_waitcnt lgkmcnt(3)
	v_mfma_f32_16x16x32_bf16 v[58:61], v[90:93], v[78:81], v[58:61]
	s_waitcnt lgkmcnt(2)
	v_mfma_f32_16x16x32_bf16 v[62:65], v[94:97], v[78:81], v[62:65]
	ds_read_b64_tr_b16 v[88:89], v131 offset:43680
	ds_read_b64_tr_b16 v[86:87], v130 offset:43680
	ds_read_b64_tr_b16 v[90:91], v130 offset:43712
	ds_read_b64_tr_b16 v[94:95], v130 offset:43744
	ds_read_b64_tr_b16 v[92:93], v131 offset:43712
	ds_read_b64_tr_b16 v[96:97], v131 offset:43744
	s_waitcnt lgkmcnt(6)
	v_mfma_f32_16x16x32_bf16 v[66:69], v[82:85], v[78:81], v[66:69]
	s_waitcnt lgkmcnt(4)
	v_mfma_f32_16x16x32_bf16 v[70:73], v[86:89], v[78:81], v[70:73]
	s_waitcnt lgkmcnt(1)
	v_mfma_f32_16x16x32_bf16 v[74:77], v[90:93], v[78:81], v[74:77]
	s_waitcnt lgkmcnt(0)
	v_mfma_f32_16x16x32_bf16 v[44:47], v[94:97], v[78:81], v[46:49]
	v_cvt_pk_bf16_f32 v8, v8, v9
	v_cvt_pk_bf16_f32 v9, v11, v12
	ds_read_b64_tr_b16 v[80:81], v131 offset:52224
	ds_read_b64_tr_b16 v[78:79], v130 offset:52224
	v_cvt_pk_bf16_f32 v10, v10, v13
	v_cvt_pk_bf16_f32 v11, v14, v15
	ds_read_b64_tr_b16 v[14:15], v131 offset:52256
	ds_read_b64_tr_b16 v[12:13], v130 offset:52256
	ds_read_b64_tr_b16 v[82:83], v130 offset:52288
	ds_read_b64_tr_b16 v[86:87], v130 offset:52320
	ds_read_b64_tr_b16 v[84:85], v131 offset:52288
	ds_read_b64_tr_b16 v[88:89], v131 offset:52320
	s_waitcnt lgkmcnt(6)
	v_mfma_f32_16x16x32_bf16 v[48:51], v[78:81], v[8:11], v[50:53]
	s_waitcnt lgkmcnt(4)
	v_mfma_f32_16x16x32_bf16 v[12:15], v[12:15], v[8:11], v[54:57]
	s_waitcnt lgkmcnt(1)
	v_mfma_f32_16x16x32_bf16 v[52:55], v[82:85], v[8:11], v[58:61]
	s_nop 0
	ds_read_b64_tr_b16 v[56:57], v130 offset:52352
	s_nop 0
	ds_read_b64_tr_b16 v[58:59], v131 offset:52352
	s_waitcnt lgkmcnt(2)
	v_mfma_f32_16x16x32_bf16 v[60:63], v[86:89], v[8:11], v[62:65]
	ds_read_b64_tr_b16 v[80:81], v131 offset:52384
	ds_read_b64_tr_b16 v[78:79], v130 offset:52384
	ds_read_b64_tr_b16 v[82:83], v130 offset:52416
	ds_read_b64_tr_b16 v[86:87], v130 offset:52448
	ds_read_b64_tr_b16 v[84:85], v131 offset:52416
	ds_read_b64_tr_b16 v[88:89], v131 offset:52448
	s_waitcnt lgkmcnt(6)
	v_mfma_f32_16x16x32_bf16 v[56:59], v[56:59], v[8:11], v[66:69]
	s_waitcnt lgkmcnt(4)
	v_mfma_f32_16x16x32_bf16 v[64:67], v[78:81], v[8:11], v[70:73]
	s_waitcnt lgkmcnt(1)
	v_mfma_f32_16x16x32_bf16 v[68:71], v[82:85], v[8:11], v[74:77]
	s_waitcnt lgkmcnt(0)
	v_mfma_f32_16x16x32_bf16 v[8:11], v[86:89], v[8:11], v[44:47]
	s_nop 2
	ds_read_b64_tr_b16 v[46:47], v131 offset:60928
	ds_read_b64_tr_b16 v[44:45], v130 offset:60928
	ds_read_b64_tr_b16 v[74:75], v131 offset:60960
	ds_read_b64_tr_b16 v[72:73], v130 offset:60960
	ds_read_b64_tr_b16 v[76:77], v130 offset:60992
	ds_read_b64_tr_b16 v[80:81], v130 offset:61024
	ds_read_b64_tr_b16 v[78:79], v131 offset:60992
	ds_read_b64_tr_b16 v[82:83], v131 offset:61024
	v_cvt_pk_bf16_f32 v4, v4, v5
	v_cvt_pk_bf16_f32 v5, v6, v7
	v_cvt_pk_bf16_f32 v6, v2, v3
	v_cvt_pk_bf16_f32 v7, v42, v1
	s_waitcnt lgkmcnt(6)
	s_nop 0
	v_mfma_f32_16x16x32_bf16 v[42:45], v[44:47], v[4:7], v[48:51]
	s_waitcnt lgkmcnt(4)
	v_mfma_f32_16x16x32_bf16 v[12:15], v[72:75], v[4:7], v[12:15]
	s_waitcnt lgkmcnt(1)
	v_mfma_f32_16x16x32_bf16 v[46:49], v[76:79], v[4:7], v[52:55]
	ds_read_b64_tr_b16 v[50:51], v130 offset:61056
	s_nop 1
	ds_read_b64_tr_b16 v[52:53], v131 offset:61056
	s_waitcnt lgkmcnt(2)
	v_mfma_f32_16x16x32_bf16 v[60:63], v[80:83], v[4:7], v[60:63]
	ds_read_b64_tr_b16 v[74:75], v131 offset:61088
	ds_read_b64_tr_b16 v[72:73], v130 offset:61088
	ds_read_b64_tr_b16 v[76:77], v130 offset:61120
	ds_read_b64_tr_b16 v[80:81], v130 offset:61152
	ds_read_b64_tr_b16 v[78:79], v131 offset:61120
	ds_read_b64_tr_b16 v[82:83], v131 offset:61152
	s_waitcnt lgkmcnt(6)
	v_mfma_f32_16x16x32_bf16 v[50:53], v[50:53], v[4:7], v[56:59]
	s_waitcnt lgkmcnt(4)
	v_mfma_f32_16x16x32_bf16 v[54:57], v[72:75], v[4:7], v[64:67]
	s_waitcnt lgkmcnt(1)
	v_mfma_f32_16x16x32_bf16 v[64:67], v[76:79], v[4:7], v[68:71]
	s_waitcnt lgkmcnt(0)
	v_mfma_f32_16x16x32_bf16 v[2:5], v[80:83], v[4:7], v[8:11]
	v_div_scale_f32 v1, s[14:15], v0, v0, 1.0
	v_rcp_f32_e32 v6, v1
	v_div_scale_f32 v7, vcc, 1.0, v0, 1.0
	v_lshl_add_u32 v58, v134, 12, v133
	v_fma_f32 v8, -v1, v6, 1.0
	v_fmac_f32_e32 v6, v8, v6
	v_mul_f32_e32 v8, v7, v6
	v_fma_f32 v9, -v1, v8, v7
	v_fmac_f32_e32 v8, v9, v6
	v_fma_f32 v1, -v1, v8, v7
	v_div_fmas_f32 v1, v1, v6, v8
	v_div_fixup_f32 v0, v1, v0, 1.0
	v_pk_mul_f32 v[10:11], v[0:1], v[44:45] op_sel_hi:[0,1]
	v_pk_mul_f32 v[6:7], v[0:1], v[42:43] op_sel_hi:[0,1]
	v_pk_mul_f32 v[14:15], v[0:1], v[14:15] op_sel_hi:[0,1]
	v_pk_mul_f32 v[8:9], v[0:1], v[12:13] op_sel_hi:[0,1]
	v_cvt_pk_bf16_f32 v6, v6, v7
	v_cvt_pk_bf16_f32 v8, v8, v9
	v_cvt_pk_bf16_f32 v7, v10, v11
	v_cvt_pk_bf16_f32 v9, v14, v15
	v_permlane16_swap_b32_e32 v6, v8
	s_nop 0
	v_permlane16_swap_b32_e32 v7, v9
	buffer_store_dwordx4 v[6:9], v58, s[4:7], 0 offen
	v_pk_mul_f32 v[10:11], v[0:1], v[48:49] op_sel_hi:[0,1]
	v_pk_mul_f32 v[12:13], v[0:1], v[62:63] op_sel_hi:[0,1]
	v_pk_mul_f32 v[6:7], v[0:1], v[46:47] op_sel_hi:[0,1]
	v_pk_mul_f32 v[8:9], v[0:1], v[60:61] op_sel_hi:[0,1]
	v_cvt_pk_bf16_f32 v6, v6, v7
	v_cvt_pk_bf16_f32 v8, v8, v9
	v_cvt_pk_bf16_f32 v7, v10, v11
	v_cvt_pk_bf16_f32 v9, v12, v13
	v_permlane16_swap_b32_e32 v6, v8
	s_nop 0
	v_permlane16_swap_b32_e32 v7, v9
	buffer_store_dwordx4 v[6:9], v58, s[4:7], 0 offen offset:64
	v_pk_mul_f32 v[10:11], v[0:1], v[52:53] op_sel_hi:[0,1]
	v_pk_mul_f32 v[12:13], v[0:1], v[56:57] op_sel_hi:[0,1]
	v_pk_mul_f32 v[6:7], v[0:1], v[50:51] op_sel_hi:[0,1]
	v_pk_mul_f32 v[8:9], v[0:1], v[54:55] op_sel_hi:[0,1]
	v_cvt_pk_bf16_f32 v6, v6, v7
	v_cvt_pk_bf16_f32 v8, v8, v9
	v_cvt_pk_bf16_f32 v7, v10, v11
	v_cvt_pk_bf16_f32 v9, v12, v13
	v_permlane16_swap_b32_e32 v6, v8
	s_nop 0
	v_permlane16_swap_b32_e32 v7, v9
	buffer_store_dwordx4 v[6:9], v58, s[4:7], 0 offen offset:128
	v_pk_mul_f32 v[4:5], v[0:1], v[4:5] op_sel_hi:[0,1]
	v_pk_mul_f32 v[2:3], v[0:1], v[2:3] op_sel_hi:[0,1]
	v_pk_mul_f32 v[6:7], v[0:1], v[66:67] op_sel_hi:[0,1]
	v_pk_mul_f32 v[8:9], v[0:1], v[64:65] op_sel_hi:[0,1]
	v_cvt_pk_bf16_f32 v0, v8, v9
	v_cvt_pk_bf16_f32 v2, v2, v3
	v_cvt_pk_bf16_f32 v1, v6, v7
	v_cvt_pk_bf16_f32 v3, v4, v5
	v_permlane16_swap_b32_e32 v0, v2
	s_nop 0
	v_permlane16_swap_b32_e32 v1, v3
	s_mov_b64 s[14:15], 16
	s_andn2_b64 vcc, exec, s[12:13]
	s_mov_b64 s[12:13], 0
	buffer_store_dwordx4 v[0:3], v58, s[4:7], 0 offen offset:192
	s_cbranch_vccz .LBB0_346
	s_add_i32 s34, s34, s3
	s_cmpk_gt_i32 s34, 0xff
	s_cbranch_scc0 .LBB0_329
